# GEMM k-loop: LDS fragment-read base addresses computed once per tile (no VALU left in the k-loop besides MFMA)
# speedup vs baseline: 1.0050x; 1.0003x over previous
; #define PG8_STAGE(bufoff, gbase, voff) do { _Pragma("unroll") for (int _i = 0; _i < 2; ++_i) \
;         __builtin_amdgcn_global_load_lds((const unsigned*)((const char*)(gbase) + (voff)[_i]), (LAS unsigned*)(lds + (bufoff) + ldsw + _i * 8192), 16, 0, 0); } while (0)
; #define PG8_LDA(dst, b, h) do { _Pragma("unroll") for (int m = 0; m < 4; ++m) _Pragma("unroll") for (int k = 0; k < 2; ++k) dst[m][k] = *(const LAS bf16x8*)(lds + PG8_SA(b, h) + aoff + m * 2048 + k * 1024); } while (0)
; #define PG8_LDB(dst, b, h) do { _Pragma("unroll") for (int n = 0; n < 2; ++n) _Pragma("unroll") for (int k = 0; k < 2; ++k) dst[n][k] = *(const LAS bf16x8*)(lds + PG8_SB(b, h) + boff + n * 2048 + k * 1024); } while (0)
; #define PG8_MMA(ai, bj, At, Bt) do { __builtin_amdgcn_s_setprio(1); _Pragma("unroll") for (int m = 0; m < 4; ++m) _Pragma("unroll") for (int n = 0; n < 2; ++n) _Pragma("unroll") for (int k = 0; k < 2; ++k) \
;         acc[ai][bj][m][n] = __builtin_amdgcn_mfma_f32_16x16x32_bf16(Bt[n][k], At[m][k], acc[ai][bj][m][n], 0, 0, 0); __builtin_amdgcn_s_setprio(0); } while (0)
; #define PG8_WAIT_V(n) asm volatile("s_waitcnt vmcnt(" #n ")" ::: "memory")
; template <class Epi>
; __device__ __forceinline__ void gemm_phase(LAS unsigned char* lds, const Gemm g, const StaticOrder& S, const Epi& E) {
;     ...
;         const bool has_next = S.next(ui + 1, nxt);
;         const char* nA = has_next ? (const char*)g.A + (size_t)nxt.pm * tstep : cA; const char* nB = has_next ? (const char*)g.Bt + (size_t)nxt.pn * tstep : cB;
;         for (int t = 0; t < nt; t += 2) {
;             const bool last = (t == nt - 2);
;             const char* a1 = cA + (size_t)(t + 1) * kstep;
;             const char* a2 = last ? nA : cA + (size_t)(t + 2) * kstep; const char* b2 = last ? nB : cB + (size_t)(t + 2) * kstep;
;             const char* a3 = a2 + kstep; const char* b3 = b2 + kstep;
;             PG8_LDB(B0, 0, 0); PG8_LDB(B1, 0, 1); PG8_SCHED; PG8_LDA(At, 0, 0); PG8_STAGE(PG8_SA(1, 1), a1 + hstep, voffA);
;             PG8_WAIT_V(8); PG8_WAIT_L(0); PG8_BAR; PG8_MMA(0, 0, At, B0); PG8_MMA(0, 1, At, B1); PG8_BAR; PG8_SCHED;
;             PG8_LDA(At, 0, 1); PG8_STAGE(PG8_SB(0, 0), b2, voffB); PG8_STAGE(PG8_SB(0, 1), b2 + hstep, voffB); PG8_STAGE(PG8_SA(0, 0), a2, voffA);
;             PG8_WAIT_V(8); PG8_WAIT_L(0); PG8_BAR; PG8_MMA(1, 0, At, B0); PG8_MMA(1, 1, At, B1); PG8_BAR; PG8_SCHED;
.LBB0_221:
	v_add_u32_e32 v216, 0x10000, v245
	v_add_u32_e32 v217, 0x14000, v245
	v_add_u32_e32 v218, 0x18000, v245
	v_add_u32_e32 v219, 0x1c000, v245
	s_add_u32 s0, s6, 0x80
	s_addc_u32 s1, s7, 0
	s_add_u32 s6, s4, 0x100
	s_addc_u32 s7, s5, 0
	s_mov_b32 s4, 0
	s_waitcnt vmcnt(0)
	s_add_i32 s71, s4, 2
	s_add_u32 s72, s0, 0x80
	s_addc_u32 s5, s1, 0
	s_cmp_eq_u32 s62, s4
	s_cselect_b32 s5, s49, s5
	s_cselect_b32 s4, s48, s72
	s_cselect_b32 s73, s51, s7
	s_cselect_b32 s72, s50, s6
	s_add_u32 s74, s72, s2
	s_addc_u32 s75, s73, 0
	s_add_u32 vcc_lo, s4, s2
	s_addc_u32 vcc_hi, s5, 0
	ds_read_b128 v[128:131], v216
	ds_read_b128 v[132:135], v216 offset:1024
	ds_read_b128 v[136:139], v216 offset:2048
	ds_read_b128 v[140:143], v216 offset:3072
	ds_read_b128 v[144:147], v217
	ds_read_b128 v[148:151], v217 offset:1024
	ds_read_b128 v[152:155], v217 offset:2048
	ds_read_b128 v[156:159], v217 offset:3072
	ds_read_b128 v[160:163], v247
	ds_read_b128 v[164:167], v247 offset:1024
	ds_read_b128 v[168:171], v247 offset:2048
	ds_read_b128 v[172:175], v247 offset:3072
	ds_read_b128 v[176:179], v247 offset:4096
	ds_read_b128 v[180:183], v247 offset:5120
	ds_read_b128 v[184:187], v247 offset:6144
	ds_read_b128 v[188:191], v247 offset:7168
	s_add_i32 m0, s55, 0xc000
	s_nop 0
	global_load_lds_dwordx4 v208, s[0:1]
	s_add_i32 m0, s55, 0xe000
	s_nop 0
	global_load_lds_dwordx4 v210, s[0:1]
	s_waitcnt vmcnt(8)
	s_waitcnt lgkmcnt(0)
	s_barrier
	s_setprio 1
	s_waitcnt lgkmcnt(0)
	v_mfma_f32_16x16x32_bf16 v[124:127], v[128:131], v[160:163], 0
	v_mfma_f32_16x16x32_bf16 v[120:123], v[136:139], v[160:163], 0
	v_mfma_f32_16x16x32_bf16 v[108:111], v[128:131], v[168:171], 0
	v_mfma_f32_16x16x32_bf16 v[104:107], v[136:139], v[168:171], 0
	v_mfma_f32_16x16x32_bf16 v[92:95], v[128:131], v[176:179], 0
	v_mfma_f32_16x16x32_bf16 v[88:91], v[136:139], v[176:179], 0
	v_mfma_f32_16x16x32_bf16 v[76:79], v[128:131], v[184:187], 0
	v_mfma_f32_16x16x32_bf16 v[72:75], v[136:139], v[184:187], 0
	v_mfma_f32_16x16x32_bf16 v[124:127], v[132:135], v[164:167], v[124:127]
	v_mfma_f32_16x16x32_bf16 v[120:123], v[140:143], v[164:167], v[120:123]
	v_mfma_f32_16x16x32_bf16 v[108:111], v[132:135], v[172:175], v[108:111]
	v_mfma_f32_16x16x32_bf16 v[104:107], v[140:143], v[172:175], v[104:107]
	v_mfma_f32_16x16x32_bf16 v[92:95], v[132:135], v[180:183], v[92:95]
	v_mfma_f32_16x16x32_bf16 v[88:91], v[140:143], v[180:183], v[88:91]
	v_mfma_f32_16x16x32_bf16 v[76:79], v[132:135], v[188:191], v[76:79]
	v_mfma_f32_16x16x32_bf16 v[72:75], v[140:143], v[188:191], v[72:75]
	s_setprio 0
	s_setprio 1
	v_mfma_f32_16x16x32_bf16 v[116:119], v[144:147], v[160:163], 0
	v_mfma_f32_16x16x32_bf16 v[112:115], v[152:155], v[160:163], 0
	v_mfma_f32_16x16x32_bf16 v[100:103], v[144:147], v[168:171], 0
	v_mfma_f32_16x16x32_bf16 v[96:99], v[152:155], v[168:171], 0
	v_mfma_f32_16x16x32_bf16 v[84:87], v[144:147], v[176:179], 0
	v_mfma_f32_16x16x32_bf16 v[80:83], v[152:155], v[176:179], 0
	v_mfma_f32_16x16x32_bf16 v[68:71], v[144:147], v[184:187], 0
	v_mfma_f32_16x16x32_bf16 v[64:67], v[152:155], v[184:187], 0
	v_mfma_f32_16x16x32_bf16 v[116:119], v[148:151], v[164:167], v[116:119]
	v_mfma_f32_16x16x32_bf16 v[112:115], v[156:159], v[164:167], v[112:115]
	v_mfma_f32_16x16x32_bf16 v[100:103], v[148:151], v[172:175], v[100:103]
	v_mfma_f32_16x16x32_bf16 v[96:99], v[156:159], v[172:175], v[96:99]
	v_mfma_f32_16x16x32_bf16 v[84:87], v[148:151], v[180:183], v[84:87]
	v_mfma_f32_16x16x32_bf16 v[80:83], v[156:159], v[180:183], v[80:83]
	v_mfma_f32_16x16x32_bf16 v[68:71], v[148:151], v[188:191], v[68:71]
	v_mfma_f32_16x16x32_bf16 v[64:67], v[156:159], v[188:191], v[64:67]
	s_setprio 0
	s_barrier
	ds_read_b128 v[160:163], v247 offset:16384
	ds_read_b128 v[164:167], v247 offset:17408
	ds_read_b128 v[168:171], v247 offset:18432
	ds_read_b128 v[172:175], v247 offset:19456
	ds_read_b128 v[176:179], v247 offset:20480
	ds_read_b128 v[180:183], v247 offset:21504
	ds_read_b128 v[184:187], v247 offset:22528
	ds_read_b128 v[188:191], v247 offset:23552
	s_add_i32 m0, s54, 0x10000
	s_nop 0
	global_load_lds_dwordx4 v192, s[72:73]
	s_add_i32 m0, s54, 0x12000
	s_nop 0
	global_load_lds_dwordx4 v204, s[72:73]
	s_add_i32 m0, s54, 0x14000
	s_nop 0
	global_load_lds_dwordx4 v192, s[74:75]
	s_add_i32 m0, s54, 0x16000
	s_nop 0
	global_load_lds_dwordx4 v204, s[74:75]
	s_mov_b32 m0, s55
	s_nop 0
	global_load_lds_dwordx4 v200, s[4:5]
	s_mov_b32 m0, s56
	s_nop 0
	global_load_lds_dwordx4 v202, s[4:5]
	s_waitcnt vmcnt(8)
	s_waitcnt lgkmcnt(0)
	s_barrier
	s_setprio 1
	s_waitcnt lgkmcnt(0)
	v_mfma_f32_16x16x32_bf16 v[60:63], v[128:131], v[160:163], 0
	v_mfma_f32_16x16x32_bf16 v[56:59], v[136:139], v[160:163], 0
	v_mfma_f32_16x16x32_bf16 v[44:47], v[128:131], v[168:171], 0
	v_mfma_f32_16x16x32_bf16 v[40:43], v[136:139], v[168:171], 0
	v_mfma_f32_16x16x32_bf16 v[28:31], v[128:131], v[176:179], 0
	v_mfma_f32_16x16x32_bf16 v[24:27], v[136:139], v[176:179], 0
	v_mfma_f32_16x16x32_bf16 v[12:15], v[128:131], v[184:187], 0
	v_mfma_f32_16x16x32_bf16 v[8:11], v[136:139], v[184:187], 0
	v_mfma_f32_16x16x32_bf16 v[60:63], v[132:135], v[164:167], v[60:63]
	v_mfma_f32_16x16x32_bf16 v[56:59], v[140:143], v[164:167], v[56:59]
	v_mfma_f32_16x16x32_bf16 v[44:47], v[132:135], v[172:175], v[44:47]
	v_mfma_f32_16x16x32_bf16 v[40:43], v[140:143], v[172:175], v[40:43]
	v_mfma_f32_16x16x32_bf16 v[28:31], v[132:135], v[180:183], v[28:31]
	v_mfma_f32_16x16x32_bf16 v[24:27], v[140:143], v[180:183], v[24:27]
	v_mfma_f32_16x16x32_bf16 v[12:15], v[132:135], v[188:191], v[12:15]
	v_mfma_f32_16x16x32_bf16 v[8:11], v[140:143], v[188:191], v[8:11]
	s_setprio 0
	s_setprio 1
	v_mfma_f32_16x16x32_bf16 v[52:55], v[144:147], v[160:163], 0
	v_mfma_f32_16x16x32_bf16 v[48:51], v[152:155], v[160:163], 0
	v_mfma_f32_16x16x32_bf16 v[36:39], v[144:147], v[168:171], 0
	v_mfma_f32_16x16x32_bf16 v[32:35], v[152:155], v[168:171], 0
	v_mfma_f32_16x16x32_bf16 v[20:23], v[144:147], v[176:179], 0
	v_mfma_f32_16x16x32_bf16 v[16:19], v[152:155], v[176:179], 0
	v_mfma_f32_16x16x32_bf16 v[4:7], v[144:147], v[184:187], 0
	v_mfma_f32_16x16x32_bf16 v[0:3], v[152:155], v[184:187], 0
	v_mfma_f32_16x16x32_bf16 v[52:55], v[148:151], v[164:167], v[52:55]
	v_mfma_f32_16x16x32_bf16 v[48:51], v[156:159], v[164:167], v[48:51]
	v_mfma_f32_16x16x32_bf16 v[36:39], v[148:151], v[172:175], v[36:39]
	v_mfma_f32_16x16x32_bf16 v[32:35], v[156:159], v[172:175], v[32:35]
	v_mfma_f32_16x16x32_bf16 v[20:23], v[148:151], v[180:183], v[20:23]
	v_mfma_f32_16x16x32_bf16 v[16:19], v[156:159], v[180:183], v[16:19]
	v_mfma_f32_16x16x32_bf16 v[4:7], v[148:151], v[188:191], v[4:7]
	v_mfma_f32_16x16x32_bf16 v[0:3], v[156:159], v[188:191], v[0:3]
	s_setprio 0
	s_barrier
; #define PG8_STAGE(bufoff, gbase, voff) do { _Pragma("unroll") for (int _i = 0; _i < 2; ++_i) \
;         __builtin_amdgcn_global_load_lds((const unsigned*)((const char*)(gbase) + (voff)[_i]), (LAS unsigned*)(lds + (bufoff) + ldsw + _i * 8192), 16, 0, 0); } while (0)
; #define PG8_LDA(dst, b, h) do { _Pragma("unroll") for (int m = 0; m < 4; ++m) _Pragma("unroll") for (int k = 0; k < 2; ++k) dst[m][k] = *(const LAS bf16x8*)(lds + PG8_SA(b, h) + aoff + m * 2048 + k * 1024); } while (0)
; #define PG8_LDB(dst, b, h) do { _Pragma("unroll") for (int n = 0; n < 2; ++n) _Pragma("unroll") for (int k = 0; k < 2; ++k) dst[n][k] = *(const LAS bf16x8*)(lds + PG8_SB(b, h) + boff + n * 2048 + k * 1024); } while (0)
; #define PG8_MMA(ai, bj, At, Bt) do { __builtin_amdgcn_s_setprio(1); _Pragma("unroll") for (int m = 0; m < 4; ++m) _Pragma("unroll") for (int n = 0; n < 2; ++n) _Pragma("unroll") for (int k = 0; k < 2; ++k) \
;         acc[ai][bj][m][n] = __builtin_amdgcn_mfma_f32_16x16x32_bf16(Bt[n][k], At[m][k], acc[ai][bj][m][n], 0, 0, 0); __builtin_amdgcn_s_setprio(0); } while (0)
; #define PG8_WAIT_V(n) asm volatile("s_waitcnt vmcnt(" #n ")" ::: "memory")
; #define PG8_WAIT_L(n) asm volatile("s_waitcnt lgkmcnt(" #n ")" ::: "memory")
; #define PG8_BAR __builtin_amdgcn_s_barrier()
; #define PG8_SCHED __builtin_amdgcn_sched_barrier(0)
; template <class Epi>
; __device__ __forceinline__ void gemm_phase(LAS unsigned char* lds, const Gemm g, const StaticOrder& S, const Epi& E) {
;     ...
;             PG8_LDB(B0, 1, 0); PG8_LDB(B1, 1, 1); PG8_SCHED; PG8_LDA(At, 1, 0); PG8_STAGE(PG8_SA(0, 1), a2 + hstep, voffA);
;             PG8_WAIT_V(8); PG8_WAIT_L(0); PG8_BAR; PG8_MMA(0, 0, At, B0); PG8_MMA(0, 1, At, B1); PG8_BAR; PG8_SCHED;
;             PG8_LDA(At, 1, 1); PG8_STAGE(PG8_SB(1, 0), b3, voffB); PG8_STAGE(PG8_SB(1, 1), b3 + hstep, voffB); PG8_STAGE(PG8_SA(1, 0), a3, voffA);
;             PG8_WAIT_V(8); PG8_WAIT_L(0); PG8_BAR; PG8_MMA(1, 0, At, B0); PG8_MMA(1, 1, At, B1); PG8_BAR; PG8_SCHED;
	ds_read_b128 v[128:131], v218
	ds_read_b128 v[132:135], v218 offset:1024
	ds_read_b128 v[136:139], v218 offset:2048
	ds_read_b128 v[140:143], v218 offset:3072
	ds_read_b128 v[144:147], v219
	ds_read_b128 v[148:151], v219 offset:1024
	ds_read_b128 v[152:155], v219 offset:2048
	ds_read_b128 v[156:159], v219 offset:3072
	ds_read_b128 v[160:163], v247 offset:32768
	ds_read_b128 v[164:167], v247 offset:33792
	ds_read_b128 v[168:171], v247 offset:34816
	ds_read_b128 v[172:175], v247 offset:35840
	ds_read_b128 v[176:179], v247 offset:36864
	ds_read_b128 v[180:183], v247 offset:37888
	ds_read_b128 v[184:187], v247 offset:38912
	ds_read_b128 v[188:191], v247 offset:39936
	s_mov_b32 m0, s57
	s_nop 0
	global_load_lds_dwordx4 v200, vcc
	s_mov_b32 m0, s58
	s_nop 0
	global_load_lds_dwordx4 v202, vcc
	s_waitcnt vmcnt(8)
	s_waitcnt lgkmcnt(0)
	s_barrier
	s_setprio 1
	s_waitcnt lgkmcnt(0)
	v_mfma_f32_16x16x32_bf16 v[124:127], v[128:131], v[160:163], v[124:127]
	v_mfma_f32_16x16x32_bf16 v[120:123], v[136:139], v[160:163], v[120:123]
	v_mfma_f32_16x16x32_bf16 v[108:111], v[128:131], v[168:171], v[108:111]
	v_mfma_f32_16x16x32_bf16 v[104:107], v[136:139], v[168:171], v[104:107]
	v_mfma_f32_16x16x32_bf16 v[92:95], v[128:131], v[176:179], v[92:95]
	v_mfma_f32_16x16x32_bf16 v[88:91], v[136:139], v[176:179], v[88:91]
	v_mfma_f32_16x16x32_bf16 v[76:79], v[128:131], v[184:187], v[76:79]
	v_mfma_f32_16x16x32_bf16 v[72:75], v[136:139], v[184:187], v[72:75]
	v_mfma_f32_16x16x32_bf16 v[124:127], v[132:135], v[164:167], v[124:127]
	v_mfma_f32_16x16x32_bf16 v[120:123], v[140:143], v[164:167], v[120:123]
	v_mfma_f32_16x16x32_bf16 v[108:111], v[132:135], v[172:175], v[108:111]
	v_mfma_f32_16x16x32_bf16 v[104:107], v[140:143], v[172:175], v[104:107]
	v_mfma_f32_16x16x32_bf16 v[92:95], v[132:135], v[180:183], v[92:95]
	v_mfma_f32_16x16x32_bf16 v[88:91], v[140:143], v[180:183], v[88:91]
	v_mfma_f32_16x16x32_bf16 v[76:79], v[132:135], v[188:191], v[76:79]
	v_mfma_f32_16x16x32_bf16 v[72:75], v[140:143], v[188:191], v[72:75]
	s_setprio 0
	s_setprio 1
	v_mfma_f32_16x16x32_bf16 v[116:119], v[144:147], v[160:163], v[116:119]
	v_mfma_f32_16x16x32_bf16 v[112:115], v[152:155], v[160:163], v[112:115]
	v_mfma_f32_16x16x32_bf16 v[100:103], v[144:147], v[168:171], v[100:103]
	v_mfma_f32_16x16x32_bf16 v[96:99], v[152:155], v[168:171], v[96:99]
	v_mfma_f32_16x16x32_bf16 v[84:87], v[144:147], v[176:179], v[84:87]
	v_mfma_f32_16x16x32_bf16 v[80:83], v[152:155], v[176:179], v[80:83]
	v_mfma_f32_16x16x32_bf16 v[68:71], v[144:147], v[184:187], v[68:71]
	v_mfma_f32_16x16x32_bf16 v[64:67], v[152:155], v[184:187], v[64:67]
	v_mfma_f32_16x16x32_bf16 v[116:119], v[148:151], v[164:167], v[116:119]
	v_mfma_f32_16x16x32_bf16 v[112:115], v[156:159], v[164:167], v[112:115]
	v_mfma_f32_16x16x32_bf16 v[100:103], v[148:151], v[172:175], v[100:103]
	v_mfma_f32_16x16x32_bf16 v[96:99], v[156:159], v[172:175], v[96:99]
	v_mfma_f32_16x16x32_bf16 v[84:87], v[148:151], v[180:183], v[84:87]
	v_mfma_f32_16x16x32_bf16 v[80:83], v[156:159], v[180:183], v[80:83]
	v_mfma_f32_16x16x32_bf16 v[68:71], v[148:151], v[188:191], v[68:71]
	v_mfma_f32_16x16x32_bf16 v[64:67], v[156:159], v[188:191], v[64:67]
	s_setprio 0
	s_barrier
	ds_read_b128 v[160:163], v247 offset:49152
	ds_read_b128 v[164:167], v247 offset:50176
	ds_read_b128 v[168:171], v247 offset:51200
	ds_read_b128 v[172:175], v247 offset:52224
	ds_read_b128 v[176:179], v247 offset:53248
	ds_read_b128 v[180:183], v247 offset:54272
	ds_read_b128 v[184:187], v247 offset:55296
	ds_read_b128 v[188:191], v247 offset:56320
	s_add_i32 m0, s54, 0x17f80
	s_nop 0
	global_load_lds_dwordx4 v192, s[72:73] offset:128
	s_add_i32 m0, s54, 0x19f80
	s_nop 0
	global_load_lds_dwordx4 v204, s[72:73] offset:128
	s_add_i32 m0, s54, 0x1bf80
	s_nop 0
	global_load_lds_dwordx4 v192, s[74:75] offset:128
	s_add_i32 m0, s54, 0x1df80
	s_nop 0
	global_load_lds_dwordx4 v204, s[74:75] offset:128
	s_add_i32 m0, s59, 0xffffff80
	s_nop 0
	global_load_lds_dwordx4 v200, s[4:5] offset:128
	s_add_i32 m0, s60, 0xffffff80
	s_nop 0
	global_load_lds_dwordx4 v202, s[4:5] offset:128
	s_waitcnt vmcnt(8)
	s_waitcnt lgkmcnt(0)
	s_barrier
	s_setprio 1
	s_waitcnt lgkmcnt(0)
	v_mfma_f32_16x16x32_bf16 v[60:63], v[128:131], v[160:163], v[60:63]
	v_mfma_f32_16x16x32_bf16 v[56:59], v[136:139], v[160:163], v[56:59]
	v_mfma_f32_16x16x32_bf16 v[44:47], v[128:131], v[168:171], v[44:47]
	v_mfma_f32_16x16x32_bf16 v[40:43], v[136:139], v[168:171], v[40:43]
	v_mfma_f32_16x16x32_bf16 v[28:31], v[128:131], v[176:179], v[28:31]
	v_mfma_f32_16x16x32_bf16 v[24:27], v[136:139], v[176:179], v[24:27]
	v_mfma_f32_16x16x32_bf16 v[12:15], v[128:131], v[184:187], v[12:15]
	v_mfma_f32_16x16x32_bf16 v[8:11], v[136:139], v[184:187], v[8:11]
	v_mfma_f32_16x16x32_bf16 v[60:63], v[132:135], v[164:167], v[60:63]
	v_mfma_f32_16x16x32_bf16 v[56:59], v[140:143], v[164:167], v[56:59]
	v_mfma_f32_16x16x32_bf16 v[44:47], v[132:135], v[172:175], v[44:47]
	v_mfma_f32_16x16x32_bf16 v[40:43], v[140:143], v[172:175], v[40:43]
	v_mfma_f32_16x16x32_bf16 v[28:31], v[132:135], v[180:183], v[28:31]
	v_mfma_f32_16x16x32_bf16 v[24:27], v[140:143], v[180:183], v[24:27]
	v_mfma_f32_16x16x32_bf16 v[12:15], v[132:135], v[188:191], v[12:15]
	v_mfma_f32_16x16x32_bf16 v[8:11], v[140:143], v[188:191], v[8:11]
	s_setprio 0
	s_setprio 1
	v_mfma_f32_16x16x32_bf16 v[52:55], v[144:147], v[160:163], v[52:55]
	v_mfma_f32_16x16x32_bf16 v[48:51], v[152:155], v[160:163], v[48:51]
	v_mfma_f32_16x16x32_bf16 v[36:39], v[144:147], v[168:171], v[36:39]
	v_mfma_f32_16x16x32_bf16 v[32:35], v[152:155], v[168:171], v[32:35]
	v_mfma_f32_16x16x32_bf16 v[20:23], v[144:147], v[176:179], v[20:23]
	v_mfma_f32_16x16x32_bf16 v[16:19], v[152:155], v[176:179], v[16:19]
	v_mfma_f32_16x16x32_bf16 v[4:7], v[144:147], v[184:187], v[4:7]
	v_mfma_f32_16x16x32_bf16 v[0:3], v[152:155], v[184:187], v[0:3]
	v_mfma_f32_16x16x32_bf16 v[52:55], v[148:151], v[164:167], v[52:55]
	v_mfma_f32_16x16x32_bf16 v[48:51], v[156:159], v[164:167], v[48:51]
	v_mfma_f32_16x16x32_bf16 v[36:39], v[148:151], v[172:175], v[36:39]
	v_mfma_f32_16x16x32_bf16 v[32:35], v[156:159], v[172:175], v[32:35]
	v_mfma_f32_16x16x32_bf16 v[20:23], v[148:151], v[180:183], v[20:23]
	v_mfma_f32_16x16x32_bf16 v[16:19], v[156:159], v[180:183], v[16:19]
	v_mfma_f32_16x16x32_bf16 v[4:7], v[148:151], v[188:191], v[4:7]
	v_mfma_f32_16x16x32_bf16 v[0:3], v[156:159], v[188:191], v[0:3]
	s_setprio 0
	s_barrier
	s_add_u32 s0, s0, 0x100
	s_addc_u32 s1, s1, 0
	s_add_u32 s6, s6, 0x100
	s_addc_u32 s7, s7, 0
	s_cmp_ge_u32 s71, s61
	s_mov_b32 s4, s71
	s_cbranch_scc1 .Lk_done
; #define PG8_STAGE(bufoff, gbase, voff) do { _Pragma("unroll") for (int _i = 0; _i < 2; ++_i) \
;         __builtin_amdgcn_global_load_lds((const unsigned*)((const char*)(gbase) + (voff)[_i]), (LAS unsigned*)(lds + (bufoff) + ldsw + _i * 8192), 16, 0, 0); } while (0)
; #define PG8_LDA(dst, b, h) do { _Pragma("unroll") for (int m = 0; m < 4; ++m) _Pragma("unroll") for (int k = 0; k < 2; ++k) dst[m][k] = *(const LAS bf16x8*)(lds + PG8_SA(b, h) + aoff + m * 2048 + k * 1024); } while (0)
; #define PG8_LDB(dst, b, h) do { _Pragma("unroll") for (int n = 0; n < 2; ++n) _Pragma("unroll") for (int k = 0; k < 2; ++k) dst[n][k] = *(const LAS bf16x8*)(lds + PG8_SB(b, h) + boff + n * 2048 + k * 1024); } while (0)
; #define PG8_MMA(ai, bj, At, Bt) do { __builtin_amdgcn_s_setprio(1); _Pragma("unroll") for (int m = 0; m < 4; ++m) _Pragma("unroll") for (int n = 0; n < 2; ++n) _Pragma("unroll") for (int k = 0; k < 2; ++k) \
;         acc[ai][bj][m][n] = __builtin_amdgcn_mfma_f32_16x16x32_bf16(Bt[n][k], At[m][k], acc[ai][bj][m][n], 0, 0, 0); __builtin_amdgcn_s_setprio(0); } while (0)
; #define PG8_WAIT_V(n) asm volatile("s_waitcnt vmcnt(" #n ")" ::: "memory")
; #define PG8_WAIT_L(n) asm volatile("s_waitcnt lgkmcnt(" #n ")" ::: "memory")
; #define PG8_BAR __builtin_amdgcn_s_barrier()
; #define PG8_SCHED __builtin_amdgcn_sched_barrier(0)
; template <class Epi>
; __device__ __forceinline__ void gemm_phase(LAS unsigned char* lds, const Gemm g, const StaticOrder& S, const Epi& E) {
;     ...
;         for (int t = 0; t < nt; t += 2) {
;             const bool last = (t == nt - 2);
;             const char* a1 = cA + (size_t)(t + 1) * kstep;
;             const char* a2 = last ? nA : cA + (size_t)(t + 2) * kstep; const char* b2 = last ? nB : cB + (size_t)(t + 2) * kstep;
;             const char* a3 = a2 + kstep; const char* b3 = b2 + kstep;
;             PG8_LDB(B0, 0, 0); PG8_LDB(B1, 0, 1); PG8_SCHED; PG8_LDA(At, 0, 0); PG8_STAGE(PG8_SA(1, 1), a1 + hstep, voffA);
;             PG8_WAIT_V(8); PG8_WAIT_L(0); PG8_BAR; PG8_MMA(0, 0, At, B0); PG8_MMA(0, 1, At, B1); PG8_BAR; PG8_SCHED;
;             PG8_LDA(At, 0, 1); PG8_STAGE(PG8_SB(0, 0), b2, voffB); PG8_STAGE(PG8_SB(0, 1), b2 + hstep, voffB); PG8_STAGE(PG8_SA(0, 0), a2, voffA);
;             PG8_WAIT_V(8); PG8_WAIT_L(0); PG8_BAR; PG8_MMA(1, 0, At, B0); PG8_MMA(1, 1, At, B1); PG8_BAR; PG8_SCHED;
.LBB0_222:
	s_add_i32 s71, s4, 2
	s_add_u32 s72, s0, 0x80
	s_addc_u32 s5, s1, 0
	s_cmp_eq_u32 s62, s4
	s_cselect_b32 s5, s49, s5
	s_cselect_b32 s4, s48, s72
	s_cselect_b32 s73, s51, s7
	s_cselect_b32 s72, s50, s6
	s_add_u32 s74, s72, s2
	s_addc_u32 s75, s73, 0
	s_add_u32 vcc_lo, s4, s2
	s_addc_u32 vcc_hi, s5, 0
	ds_read_b128 v[128:131], v216
	ds_read_b128 v[132:135], v216 offset:1024
	ds_read_b128 v[136:139], v216 offset:2048
	ds_read_b128 v[140:143], v216 offset:3072
	ds_read_b128 v[144:147], v217
	ds_read_b128 v[148:151], v217 offset:1024
	ds_read_b128 v[152:155], v217 offset:2048
	ds_read_b128 v[156:159], v217 offset:3072
	ds_read_b128 v[160:163], v247
	ds_read_b128 v[164:167], v247 offset:1024
	ds_read_b128 v[168:171], v247 offset:2048
	ds_read_b128 v[172:175], v247 offset:3072
	ds_read_b128 v[176:179], v247 offset:4096
	ds_read_b128 v[180:183], v247 offset:5120
	ds_read_b128 v[184:187], v247 offset:6144
	ds_read_b128 v[188:191], v247 offset:7168
	s_add_i32 m0, s55, 0xc000
	s_nop 0
	global_load_lds_dwordx4 v208, s[0:1]
	s_add_i32 m0, s55, 0xe000
	s_nop 0
	global_load_lds_dwordx4 v210, s[0:1]
	s_waitcnt vmcnt(8)
	s_waitcnt lgkmcnt(0)
	s_barrier
	s_setprio 1
	s_waitcnt lgkmcnt(0)
	v_mfma_f32_16x16x32_bf16 v[124:127], v[128:131], v[160:163], v[124:127]
	v_mfma_f32_16x16x32_bf16 v[120:123], v[136:139], v[160:163], v[120:123]
	v_mfma_f32_16x16x32_bf16 v[108:111], v[128:131], v[168:171], v[108:111]
	v_mfma_f32_16x16x32_bf16 v[104:107], v[136:139], v[168:171], v[104:107]
	v_mfma_f32_16x16x32_bf16 v[92:95], v[128:131], v[176:179], v[92:95]
	v_mfma_f32_16x16x32_bf16 v[88:91], v[136:139], v[176:179], v[88:91]
	v_mfma_f32_16x16x32_bf16 v[76:79], v[128:131], v[184:187], v[76:79]
	v_mfma_f32_16x16x32_bf16 v[72:75], v[136:139], v[184:187], v[72:75]
	v_mfma_f32_16x16x32_bf16 v[124:127], v[132:135], v[164:167], v[124:127]
	v_mfma_f32_16x16x32_bf16 v[120:123], v[140:143], v[164:167], v[120:123]
	v_mfma_f32_16x16x32_bf16 v[108:111], v[132:135], v[172:175], v[108:111]
	v_mfma_f32_16x16x32_bf16 v[104:107], v[140:143], v[172:175], v[104:107]
	v_mfma_f32_16x16x32_bf16 v[92:95], v[132:135], v[180:183], v[92:95]
	v_mfma_f32_16x16x32_bf16 v[88:91], v[140:143], v[180:183], v[88:91]
	v_mfma_f32_16x16x32_bf16 v[76:79], v[132:135], v[188:191], v[76:79]
	v_mfma_f32_16x16x32_bf16 v[72:75], v[140:143], v[188:191], v[72:75]
	s_setprio 0
	s_setprio 1
	v_mfma_f32_16x16x32_bf16 v[116:119], v[144:147], v[160:163], v[116:119]
	v_mfma_f32_16x16x32_bf16 v[112:115], v[152:155], v[160:163], v[112:115]
	v_mfma_f32_16x16x32_bf16 v[100:103], v[144:147], v[168:171], v[100:103]
	v_mfma_f32_16x16x32_bf16 v[96:99], v[152:155], v[168:171], v[96:99]
	v_mfma_f32_16x16x32_bf16 v[84:87], v[144:147], v[176:179], v[84:87]
	v_mfma_f32_16x16x32_bf16 v[80:83], v[152:155], v[176:179], v[80:83]
	v_mfma_f32_16x16x32_bf16 v[68:71], v[144:147], v[184:187], v[68:71]
	v_mfma_f32_16x16x32_bf16 v[64:67], v[152:155], v[184:187], v[64:67]
	v_mfma_f32_16x16x32_bf16 v[116:119], v[148:151], v[164:167], v[116:119]
	v_mfma_f32_16x16x32_bf16 v[112:115], v[156:159], v[164:167], v[112:115]
	v_mfma_f32_16x16x32_bf16 v[100:103], v[148:151], v[172:175], v[100:103]
	v_mfma_f32_16x16x32_bf16 v[96:99], v[156:159], v[172:175], v[96:99]
	v_mfma_f32_16x16x32_bf16 v[84:87], v[148:151], v[180:183], v[84:87]
	v_mfma_f32_16x16x32_bf16 v[80:83], v[156:159], v[180:183], v[80:83]
	v_mfma_f32_16x16x32_bf16 v[68:71], v[148:151], v[188:191], v[68:71]
	v_mfma_f32_16x16x32_bf16 v[64:67], v[156:159], v[188:191], v[64:67]
	s_setprio 0
	s_barrier
	ds_read_b128 v[160:163], v247 offset:16384
	ds_read_b128 v[164:167], v247 offset:17408
	ds_read_b128 v[168:171], v247 offset:18432
	ds_read_b128 v[172:175], v247 offset:19456
	ds_read_b128 v[176:179], v247 offset:20480
	ds_read_b128 v[180:183], v247 offset:21504
	ds_read_b128 v[184:187], v247 offset:22528
	ds_read_b128 v[188:191], v247 offset:23552
	s_add_i32 m0, s54, 0x10000
	s_nop 0
	global_load_lds_dwordx4 v192, s[72:73]
	s_add_i32 m0, s54, 0x12000
	s_nop 0
	global_load_lds_dwordx4 v204, s[72:73]
	s_add_i32 m0, s54, 0x14000
	s_nop 0
	global_load_lds_dwordx4 v192, s[74:75]
	s_add_i32 m0, s54, 0x16000
	s_nop 0
	global_load_lds_dwordx4 v204, s[74:75]
	s_mov_b32 m0, s55
	s_nop 0
	global_load_lds_dwordx4 v200, s[4:5]
	s_mov_b32 m0, s56
	s_nop 0
	global_load_lds_dwordx4 v202, s[4:5]
	s_waitcnt vmcnt(8)
	s_waitcnt lgkmcnt(0)
	s_barrier
	s_setprio 1
	s_waitcnt lgkmcnt(0)
	v_mfma_f32_16x16x32_bf16 v[60:63], v[128:131], v[160:163], v[60:63]
	v_mfma_f32_16x16x32_bf16 v[56:59], v[136:139], v[160:163], v[56:59]
	v_mfma_f32_16x16x32_bf16 v[44:47], v[128:131], v[168:171], v[44:47]
	v_mfma_f32_16x16x32_bf16 v[40:43], v[136:139], v[168:171], v[40:43]
	v_mfma_f32_16x16x32_bf16 v[28:31], v[128:131], v[176:179], v[28:31]
	v_mfma_f32_16x16x32_bf16 v[24:27], v[136:139], v[176:179], v[24:27]
	v_mfma_f32_16x16x32_bf16 v[12:15], v[128:131], v[184:187], v[12:15]
	v_mfma_f32_16x16x32_bf16 v[8:11], v[136:139], v[184:187], v[8:11]
	v_mfma_f32_16x16x32_bf16 v[60:63], v[132:135], v[164:167], v[60:63]
	v_mfma_f32_16x16x32_bf16 v[56:59], v[140:143], v[164:167], v[56:59]
	v_mfma_f32_16x16x32_bf16 v[44:47], v[132:135], v[172:175], v[44:47]
	v_mfma_f32_16x16x32_bf16 v[40:43], v[140:143], v[172:175], v[40:43]
	v_mfma_f32_16x16x32_bf16 v[28:31], v[132:135], v[180:183], v[28:31]
	v_mfma_f32_16x16x32_bf16 v[24:27], v[140:143], v[180:183], v[24:27]
	v_mfma_f32_16x16x32_bf16 v[12:15], v[132:135], v[188:191], v[12:15]
	v_mfma_f32_16x16x32_bf16 v[8:11], v[140:143], v[188:191], v[8:11]
	s_setprio 0
	s_setprio 1
	v_mfma_f32_16x16x32_bf16 v[52:55], v[144:147], v[160:163], v[52:55]
	v_mfma_f32_16x16x32_bf16 v[48:51], v[152:155], v[160:163], v[48:51]
	v_mfma_f32_16x16x32_bf16 v[36:39], v[144:147], v[168:171], v[36:39]
	v_mfma_f32_16x16x32_bf16 v[32:35], v[152:155], v[168:171], v[32:35]
	v_mfma_f32_16x16x32_bf16 v[20:23], v[144:147], v[176:179], v[20:23]
	v_mfma_f32_16x16x32_bf16 v[16:19], v[152:155], v[176:179], v[16:19]
	v_mfma_f32_16x16x32_bf16 v[4:7], v[144:147], v[184:187], v[4:7]
	v_mfma_f32_16x16x32_bf16 v[0:3], v[152:155], v[184:187], v[0:3]
	v_mfma_f32_16x16x32_bf16 v[52:55], v[148:151], v[164:167], v[52:55]
	v_mfma_f32_16x16x32_bf16 v[48:51], v[156:159], v[164:167], v[48:51]
	v_mfma_f32_16x16x32_bf16 v[36:39], v[148:151], v[172:175], v[36:39]
	v_mfma_f32_16x16x32_bf16 v[32:35], v[156:159], v[172:175], v[32:35]
	v_mfma_f32_16x16x32_bf16 v[20:23], v[148:151], v[180:183], v[20:23]
	v_mfma_f32_16x16x32_bf16 v[16:19], v[156:159], v[180:183], v[16:19]
	v_mfma_f32_16x16x32_bf16 v[4:7], v[148:151], v[188:191], v[4:7]
	v_mfma_f32_16x16x32_bf16 v[0:3], v[156:159], v[188:191], v[0:3]
	s_setprio 0
	s_barrier
; #define PG8_STAGE(bufoff, gbase, voff) do { _Pragma("unroll") for (int _i = 0; _i < 2; ++_i) \
;         __builtin_amdgcn_global_load_lds((const unsigned*)((const char*)(gbase) + (voff)[_i]), (LAS unsigned*)(lds + (bufoff) + ldsw + _i * 8192), 16, 0, 0); } while (0)
; #define PG8_LDA(dst, b, h) do { _Pragma("unroll") for (int m = 0; m < 4; ++m) _Pragma("unroll") for (int k = 0; k < 2; ++k) dst[m][k] = *(const LAS bf16x8*)(lds + PG8_SA(b, h) + aoff + m * 2048 + k * 1024); } while (0)
; #define PG8_LDB(dst, b, h) do { _Pragma("unroll") for (int n = 0; n < 2; ++n) _Pragma("unroll") for (int k = 0; k < 2; ++k) dst[n][k] = *(const LAS bf16x8*)(lds + PG8_SB(b, h) + boff + n * 2048 + k * 1024); } while (0)
; #define PG8_MMA(ai, bj, At, Bt) do { __builtin_amdgcn_s_setprio(1); _Pragma("unroll") for (int m = 0; m < 4; ++m) _Pragma("unroll") for (int n = 0; n < 2; ++n) _Pragma("unroll") for (int k = 0; k < 2; ++k) \
;         acc[ai][bj][m][n] = __builtin_amdgcn_mfma_f32_16x16x32_bf16(Bt[n][k], At[m][k], acc[ai][bj][m][n], 0, 0, 0); __builtin_amdgcn_s_setprio(0); } while (0)
; #define PG8_WAIT_V(n) asm volatile("s_waitcnt vmcnt(" #n ")" ::: "memory")
; #define PG8_WAIT_L(n) asm volatile("s_waitcnt lgkmcnt(" #n ")" ::: "memory")
; #define PG8_BAR __builtin_amdgcn_s_barrier()
; #define PG8_SCHED __builtin_amdgcn_sched_barrier(0)
; template <class Epi>
; __device__ __forceinline__ void gemm_phase(LAS unsigned char* lds, const Gemm g, const StaticOrder& S, const Epi& E) {
;     ...
;             PG8_LDB(B0, 1, 0); PG8_LDB(B1, 1, 1); PG8_SCHED; PG8_LDA(At, 1, 0); PG8_STAGE(PG8_SA(0, 1), a2 + hstep, voffA);
;             PG8_WAIT_V(8); PG8_WAIT_L(0); PG8_BAR; PG8_MMA(0, 0, At, B0); PG8_MMA(0, 1, At, B1); PG8_BAR; PG8_SCHED;
;             PG8_LDA(At, 1, 1); PG8_STAGE(PG8_SB(1, 0), b3, voffB); PG8_STAGE(PG8_SB(1, 1), b3 + hstep, voffB); PG8_STAGE(PG8_SA(1, 0), a3, voffA);
;             PG8_WAIT_V(8); PG8_WAIT_L(0); PG8_BAR; PG8_MMA(1, 0, At, B0); PG8_MMA(1, 1, At, B1); PG8_BAR; PG8_SCHED;
	ds_read_b128 v[128:131], v218
	ds_read_b128 v[132:135], v218 offset:1024
	ds_read_b128 v[136:139], v218 offset:2048
	ds_read_b128 v[140:143], v218 offset:3072
	ds_read_b128 v[144:147], v219
	ds_read_b128 v[148:151], v219 offset:1024
	ds_read_b128 v[152:155], v219 offset:2048
	ds_read_b128 v[156:159], v219 offset:3072
	ds_read_b128 v[160:163], v247 offset:32768
	ds_read_b128 v[164:167], v247 offset:33792
	ds_read_b128 v[168:171], v247 offset:34816
	ds_read_b128 v[172:175], v247 offset:35840
	ds_read_b128 v[176:179], v247 offset:36864
	ds_read_b128 v[180:183], v247 offset:37888
	ds_read_b128 v[184:187], v247 offset:38912
	ds_read_b128 v[188:191], v247 offset:39936
	s_mov_b32 m0, s57
	s_nop 0
	global_load_lds_dwordx4 v200, vcc
	s_mov_b32 m0, s58
	s_nop 0
	global_load_lds_dwordx4 v202, vcc
	s_waitcnt vmcnt(8)
	s_waitcnt lgkmcnt(0)
	s_barrier
	s_setprio 1
	s_waitcnt lgkmcnt(0)
	v_mfma_f32_16x16x32_bf16 v[124:127], v[128:131], v[160:163], v[124:127]
	v_mfma_f32_16x16x32_bf16 v[120:123], v[136:139], v[160:163], v[120:123]
	v_mfma_f32_16x16x32_bf16 v[108:111], v[128:131], v[168:171], v[108:111]
	v_mfma_f32_16x16x32_bf16 v[104:107], v[136:139], v[168:171], v[104:107]
	v_mfma_f32_16x16x32_bf16 v[92:95], v[128:131], v[176:179], v[92:95]
	v_mfma_f32_16x16x32_bf16 v[88:91], v[136:139], v[176:179], v[88:91]
	v_mfma_f32_16x16x32_bf16 v[76:79], v[128:131], v[184:187], v[76:79]
	v_mfma_f32_16x16x32_bf16 v[72:75], v[136:139], v[184:187], v[72:75]
	v_mfma_f32_16x16x32_bf16 v[124:127], v[132:135], v[164:167], v[124:127]
	v_mfma_f32_16x16x32_bf16 v[120:123], v[140:143], v[164:167], v[120:123]
	v_mfma_f32_16x16x32_bf16 v[108:111], v[132:135], v[172:175], v[108:111]
	v_mfma_f32_16x16x32_bf16 v[104:107], v[140:143], v[172:175], v[104:107]
	v_mfma_f32_16x16x32_bf16 v[92:95], v[132:135], v[180:183], v[92:95]
	v_mfma_f32_16x16x32_bf16 v[88:91], v[140:143], v[180:183], v[88:91]
	v_mfma_f32_16x16x32_bf16 v[76:79], v[132:135], v[188:191], v[76:79]
	v_mfma_f32_16x16x32_bf16 v[72:75], v[140:143], v[188:191], v[72:75]
	s_setprio 0
	s_setprio 1
	v_mfma_f32_16x16x32_bf16 v[116:119], v[144:147], v[160:163], v[116:119]
	v_mfma_f32_16x16x32_bf16 v[112:115], v[152:155], v[160:163], v[112:115]
	v_mfma_f32_16x16x32_bf16 v[100:103], v[144:147], v[168:171], v[100:103]
	v_mfma_f32_16x16x32_bf16 v[96:99], v[152:155], v[168:171], v[96:99]
	v_mfma_f32_16x16x32_bf16 v[84:87], v[144:147], v[176:179], v[84:87]
	v_mfma_f32_16x16x32_bf16 v[80:83], v[152:155], v[176:179], v[80:83]
	v_mfma_f32_16x16x32_bf16 v[68:71], v[144:147], v[184:187], v[68:71]
	v_mfma_f32_16x16x32_bf16 v[64:67], v[152:155], v[184:187], v[64:67]
	v_mfma_f32_16x16x32_bf16 v[116:119], v[148:151], v[164:167], v[116:119]
	v_mfma_f32_16x16x32_bf16 v[112:115], v[156:159], v[164:167], v[112:115]
	v_mfma_f32_16x16x32_bf16 v[100:103], v[148:151], v[172:175], v[100:103]
	v_mfma_f32_16x16x32_bf16 v[96:99], v[156:159], v[172:175], v[96:99]
	v_mfma_f32_16x16x32_bf16 v[84:87], v[148:151], v[180:183], v[84:87]
	v_mfma_f32_16x16x32_bf16 v[80:83], v[156:159], v[180:183], v[80:83]
	v_mfma_f32_16x16x32_bf16 v[68:71], v[148:151], v[188:191], v[68:71]
	v_mfma_f32_16x16x32_bf16 v[64:67], v[156:159], v[188:191], v[64:67]
	s_setprio 0
	s_barrier
	ds_read_b128 v[160:163], v247 offset:49152
	ds_read_b128 v[164:167], v247 offset:50176
	ds_read_b128 v[168:171], v247 offset:51200
	ds_read_b128 v[172:175], v247 offset:52224
	ds_read_b128 v[176:179], v247 offset:53248
	ds_read_b128 v[180:183], v247 offset:54272
	ds_read_b128 v[184:187], v247 offset:55296
	ds_read_b128 v[188:191], v247 offset:56320
	s_add_i32 m0, s54, 0x17f80
	s_nop 0
	global_load_lds_dwordx4 v192, s[72:73] offset:128
	s_add_i32 m0, s54, 0x19f80
	s_nop 0
	global_load_lds_dwordx4 v204, s[72:73] offset:128
	s_add_i32 m0, s54, 0x1bf80
	s_nop 0
	global_load_lds_dwordx4 v192, s[74:75] offset:128
	s_add_i32 m0, s54, 0x1df80
	s_nop 0
	global_load_lds_dwordx4 v204, s[74:75] offset:128
	s_add_i32 m0, s59, 0xffffff80
	s_nop 0
	global_load_lds_dwordx4 v200, s[4:5] offset:128
	s_add_i32 m0, s60, 0xffffff80
	s_nop 0
	global_load_lds_dwordx4 v202, s[4:5] offset:128
	s_waitcnt vmcnt(8)
	s_waitcnt lgkmcnt(0)
	s_barrier
	s_setprio 1
	s_waitcnt lgkmcnt(0)
	v_mfma_f32_16x16x32_bf16 v[60:63], v[128:131], v[160:163], v[60:63]
	v_mfma_f32_16x16x32_bf16 v[56:59], v[136:139], v[160:163], v[56:59]
	v_mfma_f32_16x16x32_bf16 v[44:47], v[128:131], v[168:171], v[44:47]
	v_mfma_f32_16x16x32_bf16 v[40:43], v[136:139], v[168:171], v[40:43]
	v_mfma_f32_16x16x32_bf16 v[28:31], v[128:131], v[176:179], v[28:31]
	v_mfma_f32_16x16x32_bf16 v[24:27], v[136:139], v[176:179], v[24:27]
	v_mfma_f32_16x16x32_bf16 v[12:15], v[128:131], v[184:187], v[12:15]
	v_mfma_f32_16x16x32_bf16 v[8:11], v[136:139], v[184:187], v[8:11]
	v_mfma_f32_16x16x32_bf16 v[60:63], v[132:135], v[164:167], v[60:63]
	v_mfma_f32_16x16x32_bf16 v[56:59], v[140:143], v[164:167], v[56:59]
	v_mfma_f32_16x16x32_bf16 v[44:47], v[132:135], v[172:175], v[44:47]
	v_mfma_f32_16x16x32_bf16 v[40:43], v[140:143], v[172:175], v[40:43]
	v_mfma_f32_16x16x32_bf16 v[28:31], v[132:135], v[180:183], v[28:31]
	v_mfma_f32_16x16x32_bf16 v[24:27], v[140:143], v[180:183], v[24:27]
	v_mfma_f32_16x16x32_bf16 v[12:15], v[132:135], v[188:191], v[12:15]
	v_mfma_f32_16x16x32_bf16 v[8:11], v[140:143], v[188:191], v[8:11]
	s_setprio 0
	s_setprio 1
	v_mfma_f32_16x16x32_bf16 v[52:55], v[144:147], v[160:163], v[52:55]
	v_mfma_f32_16x16x32_bf16 v[48:51], v[152:155], v[160:163], v[48:51]
	v_mfma_f32_16x16x32_bf16 v[36:39], v[144:147], v[168:171], v[36:39]
	v_mfma_f32_16x16x32_bf16 v[32:35], v[152:155], v[168:171], v[32:35]
	v_mfma_f32_16x16x32_bf16 v[20:23], v[144:147], v[176:179], v[20:23]
	v_mfma_f32_16x16x32_bf16 v[16:19], v[152:155], v[176:179], v[16:19]
	v_mfma_f32_16x16x32_bf16 v[4:7], v[144:147], v[184:187], v[4:7]
	v_mfma_f32_16x16x32_bf16 v[0:3], v[152:155], v[184:187], v[0:3]
	v_mfma_f32_16x16x32_bf16 v[52:55], v[148:151], v[164:167], v[52:55]
	v_mfma_f32_16x16x32_bf16 v[48:51], v[156:159], v[164:167], v[48:51]
	v_mfma_f32_16x16x32_bf16 v[36:39], v[148:151], v[172:175], v[36:39]
	v_mfma_f32_16x16x32_bf16 v[32:35], v[156:159], v[172:175], v[32:35]
	v_mfma_f32_16x16x32_bf16 v[20:23], v[148:151], v[180:183], v[20:23]
	v_mfma_f32_16x16x32_bf16 v[16:19], v[156:159], v[180:183], v[16:19]
	v_mfma_f32_16x16x32_bf16 v[4:7], v[148:151], v[188:191], v[4:7]
	v_mfma_f32_16x16x32_bf16 v[0:3], v[156:159], v[188:191], v[0:3]
	s_setprio 0
	s_barrier
	s_add_u32 s0, s0, 0x100
	s_addc_u32 s1, s1, 0
	s_add_u32 s6, s6, 0x100
	s_addc_u32 s7, s7, 0
	s_cmp_ge_u32 s71, s61
	s_mov_b32 s4, s71
	s_cbranch_scc0 .LBB0_222
